# dsa_attn: score-fragment ds_reads issued before the next-chunk index wait
# baseline (speedup 1.0000x reference)
; #define LAS __attribute__((address_space(3)))
; #define DA_RD128(dst, addr, off) asm volatile("ds_read_b128 %0, %1 offset:%2" : "=v"(dst) : "v"(addr), "i"(off) : "memory")
; #define DA_NEXT(k0_) do { __builtin_amdgcn_sched_barrier(0); if (more) DA_ISSUE_K(selv, cur ^ 1, k0_, (k0_) + DA_GRP); __builtin_amdgcn_sched_barrier(0); } while (0)
;     ...
;         for (int c = 0; c < nmax; ++c) {
;             const int cur = c & 1;
;             asm volatile("s_waitcnt vmcnt(0)" ::: "memory");
;             __builtin_amdgcn_s_barrier();
;             asm volatile("" ::: "memory"); __builtin_amdgcn_sched_barrier(0);
;             const bool more = c + 1 < nmax;
;             if (more) { const int slot = (c + 1) * 16 + fr; selv = slot < nsel ? (int)srow[slot] : 0; if (hot) selv &= 255; }
;             DA_NEXT(0);
;             const LAS unsigned char* buf = cbuf + cur * 16384;
;             f32x4 s4 = (f32x4){0.f, 0.f, 0.f, 0.f};
;             { bf16x8 af[8];
; #pragma unroll
;               for (int i4 = 0; i4 < 4; ++i4) { const unsigned sa = (unsigned)(size_t)(buf + fr * 1024 + half * 512 + (((4 * i4 + fq) ^ fr) << 4));
;                   DA_RD128(af[i4], sa, 0); DA_RD128(af[4 + i4], sa, 256); }
;               asm volatile("s_waitcnt lgkmcnt(0)" ::: "memory"); __builtin_amdgcn_sched_barrier(0);
; #pragma unroll
;               for (int ks = 0; ks < 8; ++ks) s4 = __builtin_amdgcn_mfma_f32_16x16x32_bf16(af[ks], ql[ks], s4, 0, 0, 0); }
.LBB0_768:
	v_cndmask_b32_e64 v0, 0, 1, s[14:15]
	v_cmp_ne_u32_e64 s[48:49], 1, v0
	s_andn2_b64 vcc, exec, s[14:15]
	s_and_b32 s19, s90, 0x4000
	s_add_i32 s14, s36, s19
	s_add_i32 s18, s20, s14
	v_add_u32_e32 v0, s18, v119
	v_add_u32_e32 v102, v0, v160
	ds_read_b128 v[98:101], v102 offset:0
	ds_read_b128 v[102:105], v102 offset:0x100
	v_add_u32_e32 v182, v0, v161
	ds_read_b128 v[178:181], v182 offset:0
	ds_read_b128 v[182:185], v182 offset:0x100
	v_add_u32_e32 v190, v0, v162
	ds_read_b128 v[186:189], v190 offset:0
	ds_read_b128 v[190:193], v190 offset:0x100
	v_add_u32_e32 v0, v0, v163
	ds_read_b128 v[194:197], v0 offset:0
	ds_read_b128 v[198:201], v0 offset:0x100
	s_cbranch_vccnz .LBB0_770
	s_xor_b32 s14, s19, 0x4000
	s_add_i32 s32, s36, s14
	s_waitcnt lgkmcnt(8)
	v_readlane_b32 s14, v175, s59
	s_ashr_i32 s15, s14, 31
	s_lshl_b64 s[14:15], s[14:15], 10
	v_lshl_add_u64 v[204:205], v[142:143], 0, s[14:15]
	v_readlane_b32 s14, v175, s64
	s_ashr_i32 s15, s14, 31
	s_add_i32 m0, s32, s62
	s_lshl_b64 s[14:15], s[14:15], 10
	global_load_lds_dwordx4 v[204:205], off
	v_lshl_add_u64 v[204:205], v[144:145], 0, s[14:15]
	s_add_i32 m0, s32, s65
	s_nop 0
	global_load_lds_dwordx4 v[204:205], off
.LBB0_770:
	s_waitcnt lgkmcnt(0)
	v_mfma_f32_16x16x32_bf16 v[98:101], v[98:101], v[66:69], 0
	v_mfma_f32_16x16x32_bf16 v[98:101], v[178:181], v[70:73], v[98:101]
	v_mfma_f32_16x16x32_bf16 v[98:101], v[186:189], v[74:77], v[98:101]
	v_mfma_f32_16x16x32_bf16 v[98:101], v[194:197], v[78:81], v[98:101]
	v_mfma_f32_16x16x32_bf16 v[98:101], v[102:105], v[82:85], v[98:101]
	v_mfma_f32_16x16x32_bf16 v[98:101], v[182:185], v[86:89], v[98:101]
	v_mfma_f32_16x16x32_bf16 v[98:101], v[190:193], v[90:93], v[98:101]
	v_mfma_f32_16x16x32_bf16 v[98:101], v[198:201], v[94:97], v[98:101]
	s_and_b64 vcc, exec, s[48:49]
	s_cbranch_vccnz .LBB0_772
	s_xor_b32 s14, s19, 0x4000
	s_add_i32 s24, s36, s14
	s_waitcnt lgkmcnt(0)
	v_readlane_b32 s14, v175, s66
	s_ashr_i32 s15, s14, 31
	s_lshl_b64 s[14:15], s[14:15], 10
	v_lshl_add_u64 v[102:103], v[146:147], 0, s[14:15]
	v_readlane_b32 s14, v175, s72
	s_ashr_i32 s15, s14, 31
	s_add_i32 m0, s24, s67
	s_lshl_b64 s[14:15], s[14:15], 10
	global_load_lds_dwordx4 v[102:103], off
	v_lshl_add_u64 v[102:103], v[148:149], 0, s[14:15]
	s_add_i32 m0, s24, s73
	s_nop 0
	global_load_lds_dwordx4 v[102:103], off
